# P5: upper half-workgroup waves run the W_gate|up quantisation pass before their LN1 rows (lower half unchanged) so row work and streaming overlap
# baseline (speedup 1.0000x reference)
.LBB0_1142:
	s_or_b64 exec, exec, s[4:5]
	v_readlane_b32 s6, v254, 2
	v_readlane_b32 s7, v254, 3
	v_mov_b32_e32 v249, v229
	v_mov_b32_e32 v245, v228
	v_cndmask_b32_e64 v0, 0, 1, s[6:7]
	v_cmp_ne_u32_e64 s[4:5], 1, v0
	s_andn2_b64 vcc, exec, s[6:7]
	s_waitcnt lgkmcnt(0)
	s_barrier
	s_bfe_u32 s49, s88, 0x10002
	s_cmp_eq_u32 s49, 1
	s_cbranch_scc1 .LBB0_1147
	s_cbranch_vccnz .LBB0_1147
.Lp5_ln:
	v_and_b32_e32 v0, 0xffffffc0, v234
	v_add_u32_e32 v0, 64, v0
	v_cmp_lt_i32_e32 vcc, v233, v0
	v_lshlrev_b32_e32 v134, 3, v128
	s_add_i32 s3, 0, 0x10000
	v_cndmask_b32_e32 v1, v234, v233, vcc
	v_cmp_lt_i32_e32 vcc, v232, v0
	v_lshlrev_b32_e32 v236, 2, v1
	v_add_u32_e32 v136, 0x800, v134
	v_cndmask_b32_e32 v1, v234, v232, vcc
	v_cmp_lt_i32_e32 vcc, v231, v0
	v_lshlrev_b32_e32 v237, 2, v1
	v_add_u32_e32 v138, 0xa00, v134
	v_cndmask_b32_e32 v1, v234, v231, vcc
	v_cmp_lt_i32_e32 vcc, v230, v0
	v_lshlrev_b32_e32 v238, 2, v1
	v_add_u32_e32 v140, 0xc00, v134
	v_cndmask_b32_e32 v1, v234, v230, vcc
	v_lshlrev_b32_e32 v239, 2, v1
	v_mov_b32_e32 v1, v249
	v_cmp_lt_i32_e32 vcc, v1, v0
	v_add_u32_e32 v142, 0xe00, v134
	v_lshl_add_u32 v60, v128, 5, s3
	v_cndmask_b32_e32 v1, v234, v1, vcc
	v_lshlrev_b32_e32 v240, 2, v1
	v_mov_b32_e32 v1, v245
	v_cmp_lt_i32_e32 vcc, v1, v0
	v_lshl_add_u32 v76, v136, 2, s3
	v_lshl_add_u32 v92, v138, 2, s3
	v_cndmask_b32_e32 v0, v234, v1, vcc
	v_lshl_add_u32 v108, v140, 2, s3
	v_lshl_add_u32 v124, v142, 2, s3
	v_lshlrev_b32_e32 v241, 2, v0
	ds_read_b128 v[0:3], v60
	ds_read_b128 v[4:7], v60 offset:16
	ds_read_b128 v[8:11], v60 offset:16384
	ds_read_b128 v[12:15], v60 offset:16400
	ds_read_b128 v[16:19], v60 offset:2048
	ds_read_b128 v[20:23], v60 offset:2064
	ds_read_b128 v[24:27], v60 offset:18432
	ds_read_b128 v[28:31], v60 offset:18448
	ds_read_b128 v[32:35], v60 offset:4096
	ds_read_b128 v[36:39], v60 offset:4112
	ds_read_b128 v[40:43], v60 offset:20480
	ds_read_b128 v[44:47], v60 offset:20496
	ds_read_b128 v[48:51], v60 offset:6144
	ds_read_b128 v[52:55], v60 offset:6160
	ds_read_b128 v[56:59], v60 offset:22528
	ds_read_b128 v[60:63], v60 offset:22544
	ds_read_b128 v[64:67], v76
	ds_read_b128 v[68:71], v76 offset:16
	ds_read_b128 v[72:75], v76 offset:16384
	ds_read_b128 v[76:79], v76 offset:16400
	ds_read_b128 v[80:83], v92
	ds_read_b128 v[84:87], v92 offset:16
	ds_read_b128 v[88:91], v92 offset:16384
	ds_read_b128 v[92:95], v92 offset:16400
	ds_read_b128 v[96:99], v108
	ds_read_b128 v[100:103], v108 offset:16
	ds_read_b128 v[104:107], v108 offset:16384
	ds_read_b128 v[108:111], v108 offset:16400
	ds_read_b128 v[112:115], v124
	ds_read_b128 v[116:119], v124 offset:16
	ds_read_b128 v[120:123], v124 offset:16384
	ds_read_b128 v[124:127], v124 offset:16400
	s_ashr_i32 s87, s86, 31
	s_lshl_b64 s[8:9], s[86:87], 2
	s_add_u32 s3, s8, 0xa0000
	v_ashrrev_i32_e32 v135, 31, v134
	s_addc_u32 s20, s9, 0
	s_lshl_b64 s[8:9], s[86:87], 12
	v_ashrrev_i32_e32 v137, 31, v136
	v_ashrrev_i32_e32 v139, 31, v138
	v_ashrrev_i32_e32 v141, 31, v140
	v_ashrrev_i32_e32 v143, 31, v142
	s_waitcnt lgkmcnt(14)
	v_mov_b32_e32 v130, v9
	v_mov_b32_e32 v131, v11
	v_mov_b32_e32 v9, v10
	v_mov_b32_e32 v10, v5
	v_mov_b32_e32 v11, v7
	v_mov_b32_e32 v5, v6
	v_mov_b32_e32 v6, v25
	v_mov_b32_e32 v7, v27
	v_mov_b32_e32 v25, v26
	v_mov_b32_e32 v26, v21
	v_mov_b32_e32 v27, v23
	v_mov_b32_e32 v21, v22
	v_mov_b32_e32 v22, v41
	v_mov_b32_e32 v23, v43
	v_mov_b32_e32 v41, v42
	v_mov_b32_e32 v42, v37
	v_mov_b32_e32 v43, v39
	v_mov_b32_e32 v37, v38
	v_mov_b32_e32 v38, v57
	v_mov_b32_e32 v39, v59
	v_mov_b32_e32 v57, v58
	v_mov_b32_e32 v58, v53
	v_mov_b32_e32 v59, v55
	v_mov_b32_e32 v53, v54
	s_waitcnt lgkmcnt(13)
	v_mov_b32_e32 v54, v73
	v_mov_b32_e32 v55, v75
	v_mov_b32_e32 v73, v74
	v_mov_b32_e32 v74, v69
	v_mov_b32_e32 v75, v71
	v_mov_b32_e32 v69, v70
	s_waitcnt lgkmcnt(9)
	v_mov_b32_e32 v70, v89
	v_mov_b32_e32 v71, v91
	v_mov_b32_e32 v89, v90
	v_mov_b32_e32 v90, v85
	v_mov_b32_e32 v91, v87
	v_mov_b32_e32 v85, v86
	s_waitcnt lgkmcnt(5)
	v_mov_b32_e32 v86, v105
	v_mov_b32_e32 v87, v107
	v_mov_b32_e32 v105, v106
	v_mov_b32_e32 v106, v101
	v_mov_b32_e32 v107, v103
	v_mov_b32_e32 v101, v102
	s_waitcnt lgkmcnt(1)
	v_mov_b32_e32 v102, v121
	v_mov_b32_e32 v103, v123
	v_mov_b32_e32 v121, v122
	v_mov_b32_e32 v122, v117
	v_mov_b32_e32 v123, v119
	v_mov_b32_e32 v117, v118
	v_lshl_add_u64 v[118:119], s[8:9], 0, v[134:135]
	s_lshl_b64 s[8:9], s[86:87], 13
	v_ashrrev_i32_e32 v129, 31, v128
	v_lshl_add_u64 v[136:137], v[136:137], 1, s[8:9]
	s_mov_b64 s[22:23], 0x29200000
	v_lshl_add_u64 v[138:139], v[138:139], 1, s[8:9]
	v_lshl_add_u64 v[140:141], v[140:141], 1, s[8:9]
	v_lshl_add_u64 v[142:143], v[142:143], 1, s[8:9]
	v_cmp_eq_u32_e64 s[6:7], 0, v128
	v_mov_b32_e32 v132, v1
	v_mov_b32_e32 v133, v3
	v_mov_b32_e32 v1, v2
	v_mov_b32_e32 v2, v13
	v_mov_b32_e32 v3, v15
	v_mov_b32_e32 v13, v14
	v_mov_b32_e32 v14, v17
	v_mov_b32_e32 v15, v19
	v_mov_b32_e32 v17, v18
	v_mov_b32_e32 v18, v29
	v_mov_b32_e32 v19, v31
	v_mov_b32_e32 v29, v30
	v_mov_b32_e32 v30, v33
	v_mov_b32_e32 v31, v35
	v_mov_b32_e32 v33, v34
	v_mov_b32_e32 v34, v45
	v_mov_b32_e32 v35, v47
	v_mov_b32_e32 v45, v46
	v_mov_b32_e32 v46, v49
	v_mov_b32_e32 v47, v51
	v_mov_b32_e32 v49, v50
	v_mov_b32_e32 v50, v61
	v_mov_b32_e32 v51, v63
	v_mov_b32_e32 v61, v62
	v_mov_b32_e32 v62, v65
	v_mov_b32_e32 v63, v67
	v_mov_b32_e32 v65, v66
	v_mov_b32_e32 v66, v77
	v_mov_b32_e32 v67, v79
	v_mov_b32_e32 v77, v78
	v_mov_b32_e32 v78, v81
	v_mov_b32_e32 v79, v83
	v_mov_b32_e32 v81, v82
	v_mov_b32_e32 v82, v93
	v_mov_b32_e32 v83, v95
	v_mov_b32_e32 v93, v94
	v_mov_b32_e32 v94, v97
	v_mov_b32_e32 v95, v99
	v_mov_b32_e32 v97, v98
	v_mov_b32_e32 v98, v109
	v_mov_b32_e32 v99, v111
	v_mov_b32_e32 v109, v110
	v_mov_b32_e32 v110, v113
	v_mov_b32_e32 v111, v115
	v_mov_b32_e32 v113, v114
	s_waitcnt lgkmcnt(0)
	v_mov_b32_e32 v114, v125
	v_mov_b32_e32 v115, v127
	v_mov_b32_e32 v125, v126
	s_lshl_b64 s[10:11], s[94:95], 2
	s_lshl_b64 s[14:15], s[94:95], 12
	v_lshl_add_u64 v[126:127], v[128:129], 4, s[8:9]
	s_lshl_b64 s[16:17], s[94:95], 13
	v_lshl_add_u64 v[134:135], v[134:135], 1, s[8:9]
	v_lshl_add_u64 v[136:137], v[136:137], 0, s[22:23]
	v_lshl_add_u64 v[138:139], v[138:139], 0, s[22:23]
	v_lshl_add_u64 v[140:141], v[140:141], 0, s[22:23]
	v_lshl_add_u64 v[142:143], v[142:143], 0, s[22:23]
	s_mov_b32 s21, 0x2f501000
	s_mov_b32 s22, 0xffff0000
	v_mov_b32_e32 v129, 0x3727c5ac
	s_mov_b32 s23, 0xf800000
	v_mov_b32_e32 v242, 0x260
	s_movk_i32 s24, 0x7fff
	s_mov_b32 s25, 0x29200000
	v_mov_b32_e32 v243, 0
	s_mov_b32 s26, 0x42fe0000
	s_movk_i32 s27, 0xff81
	s_mov_b32 s28, 0x40c0c00
	s_mov_b32 s29, 0x3a900000
	v_mov_b32_e32 v244, 0x7f
	s_mov_b32 s30, s86
	s_branch .LBB0_1145

.Lp5_back:
	s_mov_b32 s49, 2
	s_waitcnt vmcnt(0)
	v_readlane_b32 s6, v254, 2
	v_readlane_b32 s7, v254, 3
	s_andn2_b64 vcc, exec, s[6:7]
	s_cbranch_vccnz .LBB0_1150
	s_branch .Lp5_ln
.LBB0_1147:
	s_cmp_eq_u32 s49, 2
	s_cbranch_scc1 .LBB0_1150
	s_load_dwordx2 s[14:15], s[0:1], 0x78
	s_waitcnt lgkmcnt(0)
	s_load_dwordx2 s[16:17], s[0:1], 0x80
	s_waitcnt lgkmcnt(0)
	s_cmpk_gt_i32 s86, 0x55ff
	s_cbranch_scc1 .LBB0_1150
	v_lshlrev_b32_e32 v1, 2, v128
	v_and_b32_e32 v2, 28, v1
	v_lshlrev_b32_e32 v0, 1, v128
	v_mov_b32_e32 v5, 0
	v_lshlrev_b32_e32 v4, 2, v2
	v_and_b32_e32 v0, -16, v0
	v_lshl_add_u64 v[6:7], s[96:97], 0, v[4:5]
	s_mov_b64 s[6:7], 0x80000
	v_lshl_add_u64 v[6:7], v[6:7], 0, s[6:7]
	v_ashrrev_i32_e32 v1, 31, v0
	s_lshl_b32 s3, s86, 5
	s_lshl_b32 s22, s94, 5
	s_lshl_b32 s23, s86, 4
	s_lshl_b32 s24, s94, 4
	s_mov_b32 s21, 0
	s_mov_b32 s25, 0xac00
	v_lshlrev_b32_e32 v4, 2, v2
	s_mov_b32 s26, 0xa000
	s_mov_b32 s27, 0x15000
	s_mov_b32 s28, 0x20000
	s_mov_b32 s29, 0x2b000
	s_mov_b32 s30, 0x35000
	s_mov_b32 s31, 0x40000
	s_mov_b32 s33, 0x4b000
	s_mov_b32 s34, 0x56000
	s_mov_b32 s35, 0x60000
	s_mov_b32 s36, 0x6b000
	s_mov_b32 s37, 0x76000
	s_mov_b32 s38, 0x81000
	s_mov_b32 s39, 0x8b000
	s_mov_b32 s40, 0x96000
	s_mov_b32 s41, 0xa1000
	s_mov_b32 s42, 0x42fe0000
	s_movk_i32 s43, 0xff81
	v_mov_b32_e32 v3, 0x7f
	s_mov_b32 s44, 0x40c0c00
	s_movk_i32 s45, 0x2000
	s_mov_b32 s46, s86

.LBB0_1150:
	s_cmp_eq_u32 s49, 1
	s_cbranch_scc1 .Lp5_back
	s_waitcnt vmcnt(0)
	s_barrier
	s_mov_b64 s[6:7], exec
	v_readlane_b32 s8, v254, 8
	v_readlane_b32 s9, v254, 9
	s_and_b64 s[8:9], s[6:7], s[8:9]
	s_mov_b64 exec, s[8:9]
	s_cbranch_execz .LBB0_1202
	s_add_i32 s3, 0, 0x20160
	v_mov_b32_e32 v0, s3
	s_waitcnt vmcnt(0) expcnt(0) lgkmcnt(0)
	ds_read_b32 v2, v0
	s_add_i32 s3, 0, 0x20164
	v_mov_b32_e32 v0, s3
	ds_read_b32 v0, v0
	s_waitcnt lgkmcnt(1)
	v_cmp_ne_u32_e32 vcc, 0, v2
	s_cbranch_vccnz .LBB0_1166
	v_readlane_b32 s8, v254, 0
	v_readlane_b32 s9, v254, 1
	s_load_dwordx2 s[14:15], s[8:9], 0x4
	s_load_dword s3, s[0:1], 0xb0
	s_add_u32 s8, s96, 0x4200
	s_addc_u32 s9, s97, 0
	s_add_u32 s10, s96, 0x4400
	s_addc_u32 s11, s97, 0
	s_waitcnt lgkmcnt(0)
	s_mul_i32 s3, s14, s3
	s_add_u32 s14, s96, 0x4500
	s_mul_i32 s3, s3, s15
	s_addc_u32 s15, s97, 0
	s_add_u32 s16, s96, 0x4600
	s_addc_u32 s17, s97, 0
	s_add_u32 s20, s96, 0x4700
	s_addc_u32 s21, s97, 0
	s_add_u32 s22, s96, 0x4800
	s_addc_u32 s23, s97, 0
	s_add_u32 s24, s96, 0x4900
	s_addc_u32 s25, s97, 0
	s_add_u32 s26, s96, 0x4a00
	s_addc_u32 s27, s97, 0
	s_add_u32 s28, s96, 0x4b00
	s_addc_u32 s29, s97, 0
	s_add_u32 s30, s96, 0x4c00
	s_addc_u32 s31, s97, 0
	s_add_u32 s34, s96, 0x4d00
	s_addc_u32 s35, s97, 0
	s_add_u32 s36, s96, 0x4e00
	s_addc_u32 s37, s97, 0
	s_add_u32 s38, s96, 0x4f00
	s_addc_u32 s39, s97, 0
	s_add_u32 s40, s96, 0x5000
	s_addc_u32 s41, s97, 0
	s_add_u32 s42, s96, 0x5100
	s_addc_u32 s43, s97, 0
	s_add_u32 s44, s96, 0x5200
	s_addc_u32 s45, s97, 0
	s_add_u32 s46, s96, 0x5300
	s_addc_u32 s47, s97, 0
	s_mov_b32 s33, 1
	v_mov_b32_e32 v16, 0
	s_branch .LBB0_1154
